# v69 + P4 tail: 20 late fragment loads hoisted into dead VGPR tuples, vmcnt waits recomputed (one memory round trip instead of six)
# baseline (speedup 1.0000x reference)
; template <class Epi, int K>
; __device__ __forceinline__ void gemm_tail(LAS unsigned char* lds, const bf16_t* A, const bf16_t* Bt, const int N, const Epi& E, const int bid, const int G, const int tid_in) {
;     ...
;         const bf16_t* ap = A + (size_t)(MMAIN + i16) * K + wid * kw + 8 * kq;
;         const bf16_t* bp = Bt + (size_t)(256 * pn + 32 * wc + 8 * (i16 >> 2) + (i16 & 3)) * K + wid * kw + 8 * kq;
;         f32x4 acc[2][4][2];
; #pragma unroll
;         for (int bj = 0; bj < 2; ++bj)
; #pragma unroll
;             for (int m = 0; m < 4; ++m)
; #pragma unroll
;                 for (int n = 0; n < 2; ++n) acc[bj][m][n] = (f32x4){0.f, 0.f, 0.f, 0.f};
; #pragma unroll
;         for (int sb = 0; sb < NS; sb += 4) {
;             bf16x8 af[4][4], bf[4][2][2];
; #pragma unroll
;             for (int s = 0; s < 4; ++s) if (sb + s < NS) {
; #pragma unroll
;                 for (int m = 0; m < 4; ++m) af[s][m] = *(const bf16x8*)(ap + (size_t)(16 * m) * K + 32 * (sb + s));
; #pragma unroll
;                 for (int bj = 0; bj < 2; ++bj)
; #pragma unroll
;                     for (int n = 0; n < 2; ++n) bf[s][bj][n] = *(const bf16x8*)(bp + (size_t)(128 * bj + 4 * n) * K + 32 * (sb + s));
;             }
; #pragma unroll
;             for (int s = 0; s < 4; ++s) if (sb + s < NS) {
; #pragma unroll
;                 for (int bj = 0; bj < 2; ++bj)
; #pragma unroll
;                     for (int m = 0; m < 4; ++m)
; #pragma unroll
;                         for (int n = 0; n < 2; ++n) acc[bj][m][n] = __builtin_amdgcn_mfma_f32_16x16x32_bf16(bf[s][bj][n], af[s][m], acc[bj][m][n], 0, 0, 0);
;             }
.LBB0_793:
	s_ashr_i32 s10, s3, 2
	s_lshl_b32 s6, s3, 5
	s_and_b32 s6, s6, 0x60
	v_lshl_or_b32 v2, s10, 8, v104
	v_or_b32_e32 v2, s6, v2
	v_ashrrev_i32_e32 v3, 31, v2
	v_lshlrev_b64 v[2:3], 11, v[2:3]
	v_lshl_add_u64 v[2:3], v[70:71], 0, v[2:3]
	v_add_co_u32_e32 v4, vcc, s27, v2
	global_load_dwordx4 v[6:9], v[2:3], off
	global_load_dwordx4 v[14:17], v[68:69], off
	global_load_dwordx4 v[18:21], v[80:81], off
	v_addc_co_u32_e32 v5, vcc, 0, v3, vcc
	v_add_co_u32_e32 v12, vcc, s33, v2
	global_load_dwordx4 v[42:45], v[4:5], off
	global_load_dwordx4 v[122:125], v[2:3], off offset:64
	v_addc_co_u32_e32 v13, vcc, 0, v3, vcc
	v_add_co_u32_e32 v10, vcc, s42, v2
	global_load_dwordx4 v[58:61], v[12:13], off
	s_nop 0
	v_addc_co_u32_e32 v11, vcc, 0, v3, vcc
	global_load_dwordx4 v[110:113], v[10:11], off
	global_load_dwordx4 v[26:29], v[82:83], off
	global_load_dwordx4 v[34:37], v[84:85], off
	global_load_dwordx4 v[130:133], v[88:89], off
	global_load_dwordx4 v[134:137], v[90:91], off
	global_load_dwordx4 v[150:153], v[86:87], off
	global_load_dwordx4 v[154:157], v[10:11], off offset:64
	global_load_dwordx4 v[158:161], v[100:101], off
	global_load_dwordx4 v[162:165], v[68:69], off offset:64
	global_load_dwordx4 v[166:169], v[4:5], off offset:64
	global_load_dwordx4 v[170:173], v[12:13], off offset:64
	global_load_dwordx4 v[174:177], v[2:3], off offset:128
	global_load_dwordx4 v[178:181], v[92:93], off
	global_load_dwordx4 v[182:185], v[68:69], off offset:128
	global_load_dwordx4 v[186:189], v[94:95], off
	global_load_dwordx4 v[198:201], v[4:5], off offset:128
	global_load_dwordx4 v[202:205], v[96:97], off
	global_load_dwordx4 v[206:209], v[12:13], off offset:128
	global_load_dwordx4 v[222:225], v[10:11], off offset:128
	global_load_dwordx4 v[226:229], v[2:3], off offset:192
	global_load_dwordx4 v[230:233], v[68:69], off offset:192
	global_load_dwordx4 v[234:237], v[4:5], off offset:192
	global_load_dwordx4 v[238:241], v[98:99], off
	global_load_dwordx4 v[242:245], v[12:13], off offset:192
	global_load_dwordx4 v[246:249], v[10:11], off offset:192
	s_waitcnt vmcnt(29)
	v_mfma_f32_16x16x32_bf16 v[22:25], v[6:9], v[14:17], 0
	s_waitcnt vmcnt(28)
	v_mfma_f32_16x16x32_bf16 v[30:33], v[6:9], v[18:21], 0
	s_waitcnt vmcnt(23)
	v_mfma_f32_16x16x32_bf16 v[38:41], v[6:9], v[26:29], 0
	s_waitcnt vmcnt(22)
	v_mfma_f32_16x16x32_bf16 v[6:9], v[6:9], v[34:37], 0
	v_mfma_f32_16x16x32_bf16 v[46:49], v[42:45], v[14:17], 0
	v_mfma_f32_16x16x32_bf16 v[50:53], v[42:45], v[18:21], 0
	v_mfma_f32_16x16x32_bf16 v[54:57], v[42:45], v[26:29], 0
	v_mfma_f32_16x16x32_bf16 v[42:45], v[42:45], v[34:37], 0
	v_mfma_f32_16x16x32_bf16 v[62:65], v[58:61], v[14:17], 0
	v_mfma_f32_16x16x32_bf16 v[14:17], v[110:113], v[14:17], 0
	v_mfma_f32_16x16x32_bf16 v[114:117], v[58:61], v[18:21], 0
	v_mfma_f32_16x16x32_bf16 v[18:21], v[110:113], v[18:21], 0
	v_mfma_f32_16x16x32_bf16 v[118:121], v[58:61], v[26:29], 0
	v_mfma_f32_16x16x32_bf16 v[26:29], v[110:113], v[26:29], 0
	v_mfma_f32_16x16x32_bf16 v[58:61], v[58:61], v[34:37], 0
	v_mfma_f32_16x16x32_bf16 v[34:37], v[110:113], v[34:37], 0
	s_waitcnt vmcnt(16)
	v_mfma_f32_16x16x32_bf16 v[22:25], v[122:125], v[162:165], v[22:25]
	v_mfma_f32_16x16x32_bf16 v[30:33], v[122:125], v[150:153], v[30:33]
	v_mfma_f32_16x16x32_bf16 v[38:41], v[122:125], v[130:133], v[38:41]
	v_mfma_f32_16x16x32_bf16 v[6:9], v[122:125], v[134:137], v[6:9]
	s_waitcnt vmcnt(15)
	v_mfma_f32_16x16x32_bf16 v[46:49], v[166:169], v[162:165], v[46:49]
	v_mfma_f32_16x16x32_bf16 v[50:53], v[166:169], v[150:153], v[50:53]
	v_mfma_f32_16x16x32_bf16 v[54:57], v[166:169], v[130:133], v[54:57]
	v_mfma_f32_16x16x32_bf16 v[42:45], v[166:169], v[134:137], v[42:45]
	s_waitcnt vmcnt(14)
; #define LAS __attribute__((address_space(3)))
;     __device__ __forceinline__ void prep_commit(LAS unsigned char* lds, const PrepRegs& r, int ui, int tid) const { rs_commit(lds, r, ui, tid); }
;     __device__ __forceinline__ void prep_commit(LAS unsigned char* lds, const PrepRegs& r, int ui, int tid) const { rs_commit(lds, r, ui, tid); }
; __device__ __forceinline__ void rs_commit(LAS unsigned char* lds, const PrepRegs& r, int ui, int tid) {
;     const f32x4 s4 = r.a + r.b; float s = (s4[0] + s4[1]) + (s4[2] + s4[3]); s += __shfl_xor(s, 1);
;     if ((tid & 1) == 0) ((LAS float*)(lds + LDS_RSTAB))[(ui & 1) * 256 + (tid >> 1)] = rsqrtf(s * (1.0f / DM) + EPS);
; }
; template <class Epi, int K>
; __device__ __forceinline__ void gemm_tail(LAS unsigned char* lds, const bf16_t* A, const bf16_t* Bt, const int N, const Epi& E, const int bid, const int G, const int tid_in) {
;     ...
;             for (int s = 0; s < 4; ++s) if (sb + s < NS) {
; #pragma unroll
;                 for (int bj = 0; bj < 2; ++bj)
; #pragma unroll
;                     for (int m = 0; m < 4; ++m)
; #pragma unroll
;                         for (int n = 0; n < 2; ++n) acc[bj][m][n] = __builtin_amdgcn_mfma_f32_16x16x32_bf16(bf[s][bj][n], af[s][m], acc[bj][m][n], 0, 0, 0);
;             }
;         }
;         E.prep_commit(lds, prt, 0, tid);
	v_mfma_f32_16x16x32_bf16 v[62:65], v[170:173], v[162:165], v[62:65]
	v_mfma_f32_16x16x32_bf16 v[14:17], v[154:157], v[162:165], v[14:17]
	v_mfma_f32_16x16x32_bf16 v[110:113], v[170:173], v[150:153], v[114:117]
	v_mfma_f32_16x16x32_bf16 v[114:117], v[170:173], v[130:133], v[118:121]
	s_nop 2
	v_mfma_f32_16x16x32_bf16 v[26:29], v[154:157], v[130:133], v[26:29]
	v_mfma_f32_16x16x32_bf16 v[58:61], v[170:173], v[134:137], v[58:61]
	v_mfma_f32_16x16x32_bf16 v[34:37], v[154:157], v[134:137], v[34:37]
	v_mfma_f32_16x16x32_bf16 v[18:21], v[154:157], v[150:153], v[18:21]
	s_waitcnt vmcnt(10)
	v_mfma_f32_16x16x32_bf16 v[138:141], v[174:177], v[186:189], v[38:41]
	s_nop 2
	v_mfma_f32_16x16x32_bf16 v[30:33], v[174:177], v[178:181], v[30:33]
	s_waitcnt vmcnt(9)
	v_mfma_f32_16x16x32_bf16 v[142:145], v[198:201], v[186:189], v[54:57]
	s_waitcnt vmcnt(8)
	v_mfma_f32_16x16x32_bf16 v[6:9], v[174:177], v[202:205], v[6:9]
	s_nop 0
	v_mfma_f32_16x16x32_bf16 v[22:25], v[174:177], v[182:185], v[22:25]
	v_mfma_f32_16x16x32_bf16 v[46:49], v[198:201], v[182:185], v[46:49]
	v_mfma_f32_16x16x32_bf16 v[50:53], v[198:201], v[178:181], v[50:53]
	v_mfma_f32_16x16x32_bf16 v[42:45], v[198:201], v[202:205], v[42:45]
	s_waitcnt vmcnt(7)
	v_mfma_f32_16x16x32_bf16 v[110:113], v[206:209], v[178:181], v[110:113]
	v_mfma_f32_16x16x32_bf16 v[126:129], v[206:209], v[202:205], v[58:61]
	s_nop 2
	s_waitcnt vmcnt(6)
	v_mfma_f32_16x16x32_bf16 v[18:21], v[222:225], v[178:181], v[18:21]
	s_nop 0
	v_mfma_f32_16x16x32_bf16 v[62:65], v[206:209], v[182:185], v[62:65]
	v_mfma_f32_16x16x32_bf16 v[122:125], v[222:225], v[182:185], v[14:17]
	v_mfma_f32_16x16x32_bf16 v[114:117], v[206:209], v[186:189], v[114:117]
	v_mfma_f32_16x16x32_bf16 v[26:29], v[222:225], v[186:189], v[26:29]
	s_waitcnt vmcnt(3)
	v_mfma_f32_16x16x32_bf16 v[14:17], v[234:237], v[158:161], v[142:145]
	s_nop 2
	s_nop 0
	v_mfma_f32_16x16x32_bf16 v[54:57], v[226:229], v[230:233], v[22:25]
	v_mfma_f32_16x16x32_bf16 v[22:25], v[226:229], v[158:161], v[138:141]
	s_nop 2
	global_load_dwordx4 v[138:141], v[102:103], off
	v_mfma_f32_16x16x32_bf16 v[118:121], v[222:225], v[202:205], v[34:37]
	v_mfma_f32_16x16x32_bf16 v[46:49], v[234:237], v[230:233], v[46:49]
	s_waitcnt vmcnt(3)
	v_mfma_f32_16x16x32_bf16 v[34:37], v[234:237], v[238:241], v[50:53]
	s_waitcnt vmcnt(0)
	v_mfma_f32_16x16x32_bf16 v[2:5], v[234:237], v[138:141], v[42:45]
	v_mfma_f32_16x16x32_bf16 v[50:53], v[242:245], v[238:241], v[110:113]
	s_nop 2
	global_load_dwordx4 v[110:113], v[66:67], off offset:16
	v_mfma_f32_16x16x32_bf16 v[42:45], v[246:249], v[238:241], v[18:21]
	s_nop 2
	global_load_dwordx4 v[18:21], v[66:67], off
	v_mfma_f32_16x16x32_bf16 v[38:41], v[226:229], v[238:241], v[30:33]
	s_waitcnt vmcnt(0)
	v_pk_add_f32 v[112:113], v[20:21], v[112:113]
	v_pk_add_f32 v[110:111], v[18:19], v[110:111]
	v_mfma_f32_16x16x32_bf16 v[6:9], v[226:229], v[138:141], v[6:9]
	v_add_f32_e32 v109, v110, v111
	v_add_f32_e32 v110, v112, v113
	v_add_f32_e32 v109, v109, v110
	ds_bpermute_b32 v110, v105, v109
	v_mfma_f32_16x16x32_bf16 v[58:61], v[242:245], v[230:233], v[62:65]
	v_mfma_f32_16x16x32_bf16 v[62:65], v[246:249], v[230:233], v[122:125]
	v_mfma_f32_16x16x32_bf16 v[30:33], v[242:245], v[158:161], v[114:117]
	v_mfma_f32_16x16x32_bf16 v[26:29], v[246:249], v[158:161], v[26:29]
	v_mfma_f32_16x16x32_bf16 v[18:21], v[242:245], v[138:141], v[126:129]
	v_mfma_f32_16x16x32_bf16 v[10:13], v[246:249], v[138:141], v[118:121]
	s_and_saveexec_b64 s[8:9], s[40:41]
	s_cbranch_execz .LBB0_795
	s_waitcnt lgkmcnt(0)
	v_add_f32_e32 v109, v109, v110
	v_fmamk_f32 v109, v109, 0x3a800000, v214
	s_mov_b32 s11, 0x800000
	v_mul_f32_e32 v110, 0x4b800000, v109
	v_cmp_gt_f32_e32 vcc, s11, v109
	s_nop 1
	v_cndmask_b32_e32 v109, v109, v110, vcc
	v_rsq_f32_e32 v109, v109
	s_nop 0
	v_mul_f32_e32 v110, 0x45800000, v109
	v_cndmask_b32_e32 v109, v109, v110, vcc
	ds_write_b32 v106, v109
